# FFN-in: log2e / ln2 folded into the gate / up weight rows at conversion (as the baseline does for the q scale), SwiGLU epilogue without the per-element multiply
# speedup vs baseline: 1.0031x; 1.0020x over previous
.LBB0_22:
	v_mov_b32_e32 v112, 1.0
	v_mov_b32_e32 v113, 32
	v_mov_b32_e32 v114, 1.0
	v_mov_b32_e32 v115, 32
	v_cmp_gt_i32_e32 vcc, s47, v1
	v_cmp_lt_i32_e64 s[4:5], s48, v1
	s_and_saveexec_b64 s[6:7], s[4:5]
	s_xor_b64 s[6:7], exec, s[6:7]
	s_cbranch_execz .LBB0_40
	v_cmp_lt_u32_e64 s[4:5], s49, v1
	s_and_saveexec_b64 s[8:9], s[4:5]
	s_xor_b64 s[8:9], exec, s[8:9]
	s_cbranch_execz .LBB0_37
	v_cmp_lt_u32_e64 s[4:5], s50, v1
	v_mov_b64_e32 v[50:51], s[16:17]
	s_and_saveexec_b64 s[38:39], s[4:5]
	s_xor_b64 s[38:39], exec, s[38:39]
	s_cbranch_execz .LBB0_34
	v_cmp_lt_u32_e64 s[4:5], s51, v1
	v_mov_b64_e32 v[50:51], s[18:19]
	s_and_saveexec_b64 s[40:41], s[4:5]
	s_xor_b64 s[40:41], exec, s[40:41]
	s_cbranch_execz .LBB0_31
	v_cmp_lt_u32_e64 s[4:5], s52, v1
	v_mov_b64_e32 v[50:51], s[20:21]
	s_and_saveexec_b64 s[42:43], s[4:5]
	s_xor_b64 s[4:5], exec, s[42:43]
	v_add_u32_e32 v34, 0xffffb080, v1
	v_mov_b64_e32 v[50:51], s[22:23]
	s_or_saveexec_b64 s[4:5], s[4:5]
	v_mov_b32_e32 v52, 0x400
	v_mov_b32_e32 v69, 1.0
	v_mov_b64_e32 v[70:71], s[10:11]
	s_xor_b64 exec, exec, s[4:5]
	v_add_u32_e32 v34, 0xffffb680, v1
	v_mov_b32_e32 v52, 0xc00
	v_mov_b32_e32 v69, 0x3e38aa3b
	v_mov_b64_e32 v[70:71], s[24:25]
	s_or_b64 exec, exec, s[4:5]

.LBB0_40:
	s_andn2_saveexec_b64 s[4:5], s[6:7]
	s_cbranch_execz .LBB0_42
	v_mul_hi_i32 v34, v1, s55
	v_lshrrev_b32_e32 v35, 31, v34
	v_ashrrev_i32_e32 v34, 9, v34
	v_add_u32_e32 v36, v34, v35
	v_mov_b64_e32 v[34:35], s[12:13]
	v_mad_i64_i32 v[50:51], s[6:7], v36, s56, v[34:35]
	v_mov_b64_e32 v[34:35], s[34:35]
	v_mad_i64_i32 v[70:71], s[6:7], v36, s53, v[34:35]
	v_mul_i32_i24_e32 v34, 0xb00, v36
	v_sub_u32_e32 v34, v1, v34
	v_mov_b32_e32 v69, 0x3fb8aa3b
	v_mov_b32_e32 v112, 0x3f317218
	v_mov_b32_e32 v113, 0x58
	v_mov_b32_e32 v52, 0x1600
	v_mov_b64_e32 v[74:75], 0x400

.LBB0_60:
	s_andn2_saveexec_b64 s[8:9], s[38:39]
	s_cbranch_execz .LBB0_62
	v_mul_hi_i32 v36, v35, s55
	v_lshrrev_b32_e32 v37, 31, v36
	v_ashrrev_i32_e32 v36, 9, v36
	v_add_u32_e32 v38, v36, v37
	v_mov_b64_e32 v[36:37], s[12:13]
	v_mad_i64_i32 v[78:79], s[38:39], v38, s56, v[36:37]
	v_mov_b64_e32 v[36:37], s[34:35]
	v_mad_i64_i32 v[72:73], s[38:39], v38, s53, v[36:37]
	v_mul_i32_i24_e32 v36, 0xb00, v38
	v_sub_u32_e32 v95, v35, v36
	v_mov_b32_e32 v96, 0x3fb8aa3b
	v_mov_b32_e32 v114, 0x3f317218
	v_mov_b32_e32 v115, 0x58
	v_mov_b32_e32 v83, 0x1600
	v_mov_b64_e32 v[76:77], 0x400

.LBB0_64:
	s_or_b64 exec, exec, s[38:39]
	v_cmp_gt_i16_e64 s[8:9], v113, v101
	s_nop 1
	v_cndmask_b32_e64 v78, v112, v69, s[8:9]
	s_waitcnt vmcnt(7)
	v_pk_mul_f32 v[102:103], v[78:79], v[46:47] op_sel_hi:[0,1]
	v_pk_mul_f32 v[48:49], v[78:79], v[48:49] op_sel_hi:[0,1]
	v_add_u32_e32 v47, 0xe008, v92
	ds_write2_b32 v47, v48, v49 offset1:1
	s_waitcnt vmcnt(6)
	v_pk_mul_f32 v[48:49], v[78:79], v[34:35] op_sel_hi:[0,1]
	v_add_u32_e32 v35, 0xe420, v92
	ds_write2_b32 v35, v48, v49 offset1:1
	v_pk_mul_f32 v[48:49], v[78:79], v[36:37] op_sel_hi:[0,1]
	v_add_u32_e32 v36, 0xe428, v92
	ds_write2_b32 v36, v48, v49 offset1:1
	s_waitcnt vmcnt(5)
	v_pk_mul_f32 v[48:49], v[78:79], v[54:55] op_sel_hi:[0,1]
	v_add_u32_e32 v37, 0xe840, v92
	ds_write2_b32 v37, v48, v49 offset1:1
	v_pk_mul_f32 v[54:55], v[78:79], v[56:57] op_sel_hi:[0,1]
	v_add_u32_e32 v48, 0xe848, v92
	ds_write2_b32 v48, v54, v55 offset1:1
	s_waitcnt vmcnt(4)
	v_pk_mul_f32 v[54:55], v[78:79], v[38:39] op_sel_hi:[0,1]
	v_add_u32_e32 v38, 0xec60, v92
	v_pk_mul_f32 v[40:41], v[78:79], v[40:41] op_sel_hi:[0,1]
	v_add_u32_e32 v39, 0xec68, v92
	ds_write2_b32 v38, v54, v55 offset1:1
	ds_write2_b32 v39, v40, v41 offset1:1
	s_waitcnt vmcnt(3)
	v_pk_mul_f32 v[54:55], v[78:79], v[58:59] op_sel_hi:[0,1]
	v_add_u32_e32 v40, 0xf080, v92
	ds_write2_b32 v40, v54, v55 offset1:1
	v_pk_mul_f32 v[54:55], v[78:79], v[60:61] op_sel_hi:[0,1]
	v_add_u32_e32 v41, 0xf088, v92
	ds_write2_b32 v41, v54, v55 offset1:1
	s_waitcnt vmcnt(2)
	v_pk_mul_f32 v[54:55], v[78:79], v[42:43] op_sel_hi:[0,1]
	v_add_u32_e32 v42, 0xf4a0, v92
	v_pk_mul_f32 v[44:45], v[78:79], v[44:45] op_sel_hi:[0,1]
	v_add_u32_e32 v43, 0xf4a8, v92
	ds_write2_b32 v42, v54, v55 offset1:1
	ds_write2_b32 v43, v44, v45 offset1:1
	s_waitcnt vmcnt(1)
	v_pk_mul_f32 v[54:55], v[78:79], v[62:63] op_sel_hi:[0,1]
	v_add_u32_e32 v44, 0xf8c0, v92
	s_waitcnt vmcnt(0)
	v_pk_mul_f32 v[50:51], v[78:79], v[50:51] op_sel_hi:[0,1]
	v_add_u32_e32 v49, 0xfce0, v92
	v_add_u32_e32 v46, 0xe000, v92
	ds_write2_b32 v44, v54, v55 offset1:1
	v_pk_mul_f32 v[54:55], v[78:79], v[64:65] op_sel_hi:[0,1]
	v_add_u32_e32 v45, 0xf8c8, v92
	ds_write2_b32 v49, v50, v51 offset1:1
	v_pk_mul_f32 v[52:53], v[78:79], v[52:53] op_sel_hi:[0,1]
	v_add_u32_e32 v50, 0xfce8, v92
	ds_write2_b32 v46, v102, v103 offset1:1
	ds_write2_b32 v45, v54, v55 offset1:1
	ds_write2_b32 v50, v52, v53 offset1:1
	s_waitcnt lgkmcnt(0)
	s_and_saveexec_b64 s[8:9], vcc
	s_cbranch_execz .LBB0_66
	v_mul_i32_i24_sdwa v34, sext(v101), s57 dst_sel:DWORD dst_unused:UNUSED_PAD src0_sel:WORD_0 src1_sel:DWORD
	v_lshrrev_b32_e32 v51, 31, v34
	v_ashrrev_i32_e32 v34, 18, v34
	v_add_u16_e32 v34, v34, v51
	v_mul_i32_i24_e32 v51, 0xba3, v80
	v_lshrrev_b32_e32 v52, 31, v51
	v_lshrrev_b32_e32 v51, 23, v51
	v_add_u16_e32 v51, v51, v52
	v_mul_lo_u16_e32 v51, 0xb00, v51
	v_sub_u16_e32 v51, v80, v51
	v_ashrrev_i16_e32 v52, 15, v51
	v_lshrrev_b16_e32 v52, 9, v52
	v_add_u16_e32 v52, v51, v52
	v_ashrrev_i16_e32 v53, 7, v52
	v_and_b32_e32 v52, 0xffffff80, v52
	v_sub_u16_e32 v51, v51, v52
	v_lshlrev_b32_sdwa v53, v93, sext(v53) dst_sel:DWORD dst_unused:UNUSED_PAD src0_sel:DWORD src1_sel:WORD_0
	v_lshlrev_b32_sdwa v34, v94, sext(v34) dst_sel:DWORD dst_unused:UNUSED_PAD src0_sel:DWORD src1_sel:WORD_0
	v_bfe_i32 v51, v51, 0, 16
	v_add3_u32 v80, v34, v51, v53
.LBB0_66:
	s_or_b64 exec, exec, s[8:9]
	v_add_u32_e32 v34, 0xe000, v88
	ds_read2_b32 v[56:57], v34 offset0:33 offset1:41
	ds_read2_b32 v[58:59], v34 offset1:8
	ds_read2_b32 v[60:61], v34 offset0:66 offset1:74
	ds_read2_b32 v[62:63], v34 offset0:99 offset1:107
	ds_read2_b32 v[64:65], v34 offset0:132 offset1:140
	ds_read2_b32 v[78:79], v34 offset0:165 offset1:173
	ds_read2_b32 v[102:103], v34 offset0:198 offset1:206
	ds_read2_b32 v[104:105], v34 offset0:231 offset1:239
	v_add_u32_e32 v51, v80, v84
	s_waitcnt lgkmcnt(6)
	v_cvt_pk_bf16_f32 v52, v58, v56
	v_ashrrev_i32_e32 v56, 31, v51
	v_mul_lo_u32 v56, v74, v56
	v_mul_lo_u32 v58, v75, v51
	v_mad_u64_u32 v[106:107], s[8:9], v74, v51, 0
	v_ashrrev_i32_e32 v83, 31, v82
	v_add3_u32 v107, v107, v56, v58
	v_lshl_add_u64 v[106:107], v[106:107], 1, v[70:71]
	v_lshlrev_b64 v[82:83], 1, v[82:83]
	v_lshl_add_u64 v[106:107], v[106:107], 0, v[82:83]
	v_mov_b32_e32 v69, v67
	v_add_u32_e32 v51, v80, v85
	s_waitcnt lgkmcnt(4)
	v_cvt_pk_bf16_f32 v53, v60, v62
	s_waitcnt lgkmcnt(2)
	v_cvt_pk_bf16_f32 v54, v64, v78
	s_waitcnt lgkmcnt(0)
	v_cvt_pk_bf16_f32 v55, v102, v104
	v_lshl_add_u64 v[106:107], v[106:107], 0, v[68:69]
	v_ashrrev_i32_e32 v56, 31, v51
	global_store_dwordx4 v[106:107], v[52:55], off
	v_mul_lo_u32 v58, v74, v56
	s_nop 0
	v_cvt_pk_bf16_f32 v52, v59, v57
	v_mul_lo_u32 v59, v75, v51
	v_mad_u64_u32 v[56:57], s[8:9], v74, v51, 0
	v_add3_u32 v57, v57, v58, v59
	v_lshl_add_u64 v[56:57], v[56:57], 1, v[70:71]
	v_lshl_add_u64 v[56:57], v[56:57], 0, v[82:83]
	v_cvt_pk_bf16_f32 v53, v61, v63
	v_cvt_pk_bf16_f32 v54, v65, v79
	v_cvt_pk_bf16_f32 v55, v103, v105
	v_lshl_add_u64 v[56:57], v[56:57], 0, v[68:69]
	v_add_u32_e32 v51, v80, v86
	ds_read2_b32 v[58:59], v34 offset0:16 offset1:24
	ds_read2_b32 v[60:61], v34 offset0:49 offset1:57
	ds_read2_b32 v[62:63], v34 offset0:82 offset1:90
	ds_read2_b32 v[64:65], v34 offset0:115 offset1:123
	ds_read2_b32 v[78:79], v34 offset0:148 offset1:156
	ds_read2_b32 v[102:103], v34 offset0:181 offset1:189
	ds_read2_b32 v[104:105], v34 offset0:214 offset1:222
	ds_read2_b32 v[106:107], v34 offset0:247 offset1:255
	global_store_dwordx4 v[56:57], v[52:55], off
	v_ashrrev_i32_e32 v56, 31, v51
	s_waitcnt lgkmcnt(6)
	v_cvt_pk_bf16_f32 v52, v58, v60
	v_mul_lo_u32 v58, v74, v56
	v_mul_lo_u32 v60, v75, v51
	v_mad_u64_u32 v[56:57], s[8:9], v74, v51, 0
	v_add3_u32 v57, v57, v58, v60
	v_lshl_add_u64 v[56:57], v[56:57], 1, v[70:71]
	v_lshl_add_u64 v[56:57], v[56:57], 0, v[82:83]
	s_waitcnt lgkmcnt(4)
	v_cvt_pk_bf16_f32 v53, v62, v64
	s_waitcnt lgkmcnt(2)
	v_cvt_pk_bf16_f32 v54, v78, v102
	s_waitcnt lgkmcnt(0)
	v_cvt_pk_bf16_f32 v55, v104, v106
	v_lshl_add_u64 v[56:57], v[56:57], 0, v[68:69]
	v_add_u32_e32 v51, v80, v87
	global_store_dwordx4 v[56:57], v[52:55], off
	v_ashrrev_i32_e32 v56, 31, v51
	v_mul_lo_u32 v58, v74, v56
	v_cvt_pk_bf16_f32 v52, v59, v61
	v_mul_lo_u32 v59, v75, v51
	v_mad_u64_u32 v[56:57], s[8:9], v74, v51, 0
	v_add3_u32 v57, v57, v58, v59
	v_lshl_add_u64 v[56:57], v[56:57], 1, v[70:71]
	v_lshl_add_u64 v[56:57], v[56:57], 0, v[82:83]
	v_cvt_pk_bf16_f32 v53, v63, v65
	v_cvt_pk_bf16_f32 v54, v79, v103
	v_cvt_pk_bf16_f32 v55, v105, v107
	v_lshl_add_u64 v[56:57], v[56:57], 0, v[68:69]
	global_store_dwordx4 v[56:57], v[52:55], off
	s_waitcnt lgkmcnt(0)
	s_and_saveexec_b64 s[8:9], s[4:5]
	s_cbranch_execz .LBB0_21
	v_rcp_iflag_f32_e32 v51, v99
	s_nop 0
	v_mul_f32_e32 v51, 0x4f7ffffe, v51
	v_cvt_u32_f32_e32 v51, v51
	v_mul_lo_u32 v52, v100, v51
	v_mul_hi_u32 v52, v51, v52
	v_add_u32_e32 v51, v51, v52
	v_mul_hi_u32 v51, v98, v51
	v_mul_lo_u32 v52, v51, v81
	v_sub_u32_e32 v52, v98, v52
	v_add_u32_e32 v53, 1, v51
	v_cmp_ge_u32_e32 vcc, v52, v81
	s_nop 1
	v_cndmask_b32_e32 v51, v51, v53, vcc
	v_sub_u32_e32 v53, v52, v81
	v_cndmask_b32_e32 v52, v52, v53, vcc
	v_add_u32_e32 v53, 1, v51
	v_cmp_ge_u32_e32 vcc, v52, v81
	s_nop 1
	v_cndmask_b32_e32 v51, v51, v53, vcc
	v_xor_b32_e32 v51, v51, v97
	v_sub_u32_e32 v51, v51, v97
	v_mul_lo_u32 v52, v51, v81
	v_sub_u32_e32 v52, v95, v52
	v_cmp_gt_i32_e32 vcc, v115, v52
	s_nop 1
	v_cndmask_b32_e32 v54, v114, v96, vcc
	v_pk_mul_f32 v[56:57], v[2:3], v[54:55] op_sel_hi:[1,0]
	ds_write2_b32 v46, v56, v57 offset1:1
	v_pk_mul_f32 v[56:57], v[4:5], v[54:55] op_sel_hi:[1,0]
	ds_write2_b32 v47, v56, v57 offset1:1
	v_pk_mul_f32 v[46:47], v[6:7], v[54:55] op_sel_hi:[1,0]
	ds_write2_b32 v35, v46, v47 offset1:1
	v_pk_mul_f32 v[46:47], v[8:9], v[54:55] op_sel_hi:[1,0]
	ds_write2_b32 v36, v46, v47 offset1:1
	v_pk_mul_f32 v[46:47], v[10:11], v[54:55] op_sel_hi:[1,0]
	ds_write2_b32 v37, v46, v47 offset1:1
	v_pk_mul_f32 v[36:37], v[12:13], v[54:55] op_sel_hi:[1,0]
	ds_write2_b32 v48, v36, v37 offset1:1
	v_pk_mul_f32 v[36:37], v[14:15], v[54:55] op_sel_hi:[1,0]
	ds_write2_b32 v38, v36, v37 offset1:1
	v_pk_mul_f32 v[36:37], v[16:17], v[54:55] op_sel_hi:[1,0]
	ds_write2_b32 v39, v36, v37 offset1:1
	v_pk_mul_f32 v[36:37], v[18:19], v[54:55] op_sel_hi:[1,0]
	ds_write2_b32 v40, v36, v37 offset1:1
	v_pk_mul_f32 v[36:37], v[20:21], v[54:55] op_sel_hi:[1,0]
	ds_write2_b32 v41, v36, v37 offset1:1
	v_pk_mul_f32 v[36:37], v[22:23], v[54:55] op_sel_hi:[1,0]
	ds_write2_b32 v42, v36, v37 offset1:1
	v_pk_mul_f32 v[36:37], v[24:25], v[54:55] op_sel_hi:[1,0]
	ds_write2_b32 v43, v36, v37 offset1:1
	v_pk_mul_f32 v[36:37], v[26:27], v[54:55] op_sel_hi:[1,0]
	ds_write2_b32 v44, v36, v37 offset1:1
	v_pk_mul_f32 v[36:37], v[28:29], v[54:55] op_sel_hi:[1,0]
	ds_write2_b32 v45, v36, v37 offset1:1
	v_pk_mul_f32 v[36:37], v[30:31], v[54:55] op_sel_hi:[1,0]
	ds_write2_b32 v49, v36, v37 offset1:1
	v_pk_mul_f32 v[36:37], v[32:33], v[54:55] op_sel_hi:[1,0]
	ds_write2_b32 v50, v36, v37 offset1:1
	s_waitcnt lgkmcnt(0)
	v_lshlrev_b32_e32 v35, 5, v52
	s_and_saveexec_b64 s[4:5], s[6:7]
	s_cbranch_execz .LBB0_20
	v_mul_i32_i24_e32 v36, 0xba3, v52
	v_lshrrev_b32_e32 v37, 31, v36
	v_ashrrev_i32_e32 v36, 18, v36
	v_add_u16_e32 v36, v36, v37
	v_mul_i32_i24_e32 v37, 0xba3, v35
	v_lshrrev_b32_e32 v38, 31, v37
	v_lshrrev_b32_e32 v37, 23, v37
	v_add_u16_e32 v37, v37, v38
	v_mul_lo_u16_e32 v37, 0xb00, v37
	v_sub_u16_e32 v35, v35, v37
	v_ashrrev_i16_e32 v37, 15, v35
	v_lshrrev_b16_e32 v37, 9, v37
	v_add_u16_e32 v37, v35, v37
	v_ashrrev_i16_e32 v38, 7, v37
	v_and_b32_e32 v37, 0xffffff80, v37
	v_sub_u16_e32 v35, v35, v37
	v_lshlrev_b32_sdwa v38, v93, sext(v38) dst_sel:DWORD dst_unused:UNUSED_PAD src0_sel:DWORD src1_sel:WORD_0
	v_lshlrev_b32_sdwa v36, v94, sext(v36) dst_sel:DWORD dst_unused:UNUSED_PAD src0_sel:DWORD src1_sel:WORD_0
	v_bfe_i32 v35, v35, 0, 16
	v_add3_u32 v35, v36, v35, v38
	s_branch .LBB0_20

.LBB0_216:
	v_lshl_add_u32 v181, s1, 8, v154
	v_lshl_or_b32 v170, s0, 7, v156
	v_readlane_b32 s0, v254, 45
	v_readlane_b32 s1, v254, 46
	s_movk_i32 s3, 0x1600
	s_mov_b64 s[68:69], 0x16000
	s_mov_b64 s[70:71], 0x6e000
	s_andn2_b64 vcc, exec, s[42:43]
	s_mov_b64 s[16:17], -1
	v_ashrrev_i32_e32 v171, 31, v170
	v_mov_b64_e32 v[152:153], s[0:1]
	v_lshlrev_b64 v[170:171], 1, v[170:171]
	v_mad_i64_i32 v[182:183], s[0:1], v181, s3, v[152:153]
	s_nop 0
	v_lshl_add_u64 v[182:183], v[182:183], 0, v[170:171]
	v_exp_f32_e64 v152, -v124
	v_exp_f32_e64 v153, -v125
	v_exp_f32_e64 v178, -v126
	v_exp_f32_e64 v179, -v127
	v_exp_f32_e64 v246, -v120
	v_exp_f32_e64 v247, -v121
	v_exp_f32_e64 v248, -v122
	v_exp_f32_e64 v249, -v123
	v_mul_f32_e32 v124, v124, v116
	v_mul_f32_e32 v125, v125, v117
	v_mul_f32_e32 v126, v126, v118
	v_mul_f32_e32 v127, v127, v119
	v_mul_f32_e32 v120, v120, v112
	v_mul_f32_e32 v121, v121, v113
	v_mul_f32_e32 v122, v122, v114
	v_mul_f32_e32 v123, v123, v115
	v_add_f32_e32 v152, 1.0, v152
	v_add_f32_e32 v153, 1.0, v153
	v_add_f32_e32 v178, 1.0, v178
	v_add_f32_e32 v179, 1.0, v179
	v_add_f32_e32 v246, 1.0, v246
	v_add_f32_e32 v247, 1.0, v247
	v_add_f32_e32 v248, 1.0, v248
	v_add_f32_e32 v249, 1.0, v249
	v_rcp_f32_e32 v152, v152
	v_rcp_f32_e32 v153, v153
	v_rcp_f32_e32 v178, v178
	v_rcp_f32_e32 v179, v179
	v_rcp_f32_e32 v246, v246
	v_rcp_f32_e32 v247, v247
	v_rcp_f32_e32 v248, v248
	v_rcp_f32_e32 v249, v249
	v_mul_f32_e32 v124, v124, v152
	v_mul_f32_e32 v125, v125, v153
	v_mul_f32_e32 v126, v126, v178
	v_mul_f32_e32 v127, v127, v179
	v_mul_f32_e32 v120, v120, v246
	v_mul_f32_e32 v121, v121, v247
	v_mul_f32_e32 v122, v122, v248
	v_mul_f32_e32 v123, v123, v249
	v_cvt_pk_bf16_f32 v116, v124, v125
	v_cvt_pk_bf16_f32 v117, v126, v127
	v_cvt_pk_bf16_f32 v118, v120, v121
	v_cvt_pk_bf16_f32 v119, v122, v123
	global_store_dwordx4 v[182:183], v[116:119], off
	v_exp_f32_e64 v152, -v108
	v_exp_f32_e64 v153, -v109
	v_exp_f32_e64 v178, -v110
	v_exp_f32_e64 v179, -v111
	v_exp_f32_e64 v246, -v104
	v_exp_f32_e64 v247, -v105
	v_exp_f32_e64 v248, -v106
	v_exp_f32_e64 v249, -v107
	v_mul_f32_e32 v108, v108, v100
	v_mul_f32_e32 v109, v109, v101
	v_mul_f32_e32 v110, v110, v102
	v_mul_f32_e32 v111, v111, v103
	v_mul_f32_e32 v104, v104, v96
	v_mul_f32_e32 v105, v105, v97
	v_mul_f32_e32 v106, v106, v98
	v_mul_f32_e32 v107, v107, v99
	v_add_f32_e32 v152, 1.0, v152
	v_add_f32_e32 v153, 1.0, v153
	v_add_f32_e32 v178, 1.0, v178
	v_add_f32_e32 v179, 1.0, v179
	v_add_f32_e32 v246, 1.0, v246
	v_add_f32_e32 v247, 1.0, v247
	v_add_f32_e32 v248, 1.0, v248
	v_add_f32_e32 v249, 1.0, v249
	v_rcp_f32_e32 v152, v152
	v_rcp_f32_e32 v153, v153
	v_rcp_f32_e32 v178, v178
	v_rcp_f32_e32 v179, v179
	v_rcp_f32_e32 v246, v246
	v_rcp_f32_e32 v247, v247
	v_rcp_f32_e32 v248, v248
	v_rcp_f32_e32 v249, v249
	v_mul_f32_e32 v108, v108, v152
	v_mul_f32_e32 v109, v109, v153
	v_mul_f32_e32 v110, v110, v178
	v_mul_f32_e32 v111, v111, v179
	v_mul_f32_e32 v104, v104, v246
	v_mul_f32_e32 v105, v105, v247
	v_mul_f32_e32 v106, v106, v248
	v_mul_f32_e32 v107, v107, v249
	v_cvt_pk_bf16_f32 v100, v108, v109
	v_cvt_pk_bf16_f32 v101, v110, v111
	v_cvt_pk_bf16_f32 v102, v104, v105
	v_cvt_pk_bf16_f32 v103, v106, v107
	v_lshl_add_u64 v[182:183], v[182:183], 0, s[68:69]
	s_nop 0
	global_store_dwordx4 v[182:183], v[100:103], off
	v_exp_f32_e64 v152, -v92
	v_exp_f32_e64 v153, -v93
	v_exp_f32_e64 v178, -v94
	v_exp_f32_e64 v179, -v95
	v_exp_f32_e64 v246, -v88
	v_exp_f32_e64 v247, -v89
	v_exp_f32_e64 v248, -v90
	v_exp_f32_e64 v249, -v91
	v_mul_f32_e32 v92, v92, v84
	v_mul_f32_e32 v93, v93, v85
	v_mul_f32_e32 v94, v94, v86
	v_mul_f32_e32 v95, v95, v87
	v_mul_f32_e32 v88, v88, v80
	v_mul_f32_e32 v89, v89, v81
	v_mul_f32_e32 v90, v90, v82
	v_mul_f32_e32 v91, v91, v83
	v_add_f32_e32 v152, 1.0, v152
	v_add_f32_e32 v153, 1.0, v153
	v_add_f32_e32 v178, 1.0, v178
	v_add_f32_e32 v179, 1.0, v179
	v_add_f32_e32 v246, 1.0, v246
	v_add_f32_e32 v247, 1.0, v247
	v_add_f32_e32 v248, 1.0, v248
	v_add_f32_e32 v249, 1.0, v249
	v_rcp_f32_e32 v152, v152
	v_rcp_f32_e32 v153, v153
	v_rcp_f32_e32 v178, v178
	v_rcp_f32_e32 v179, v179
	v_rcp_f32_e32 v246, v246
	v_rcp_f32_e32 v247, v247
	v_rcp_f32_e32 v248, v248
	v_rcp_f32_e32 v249, v249
	v_mul_f32_e32 v92, v92, v152
	v_mul_f32_e32 v93, v93, v153
	v_mul_f32_e32 v94, v94, v178
	v_mul_f32_e32 v95, v95, v179
	v_mul_f32_e32 v88, v88, v246
	v_mul_f32_e32 v89, v89, v247
	v_mul_f32_e32 v90, v90, v248
	v_mul_f32_e32 v91, v91, v249
	v_cvt_pk_bf16_f32 v84, v92, v93
	v_cvt_pk_bf16_f32 v85, v94, v95
	v_cvt_pk_bf16_f32 v86, v88, v89
	v_cvt_pk_bf16_f32 v87, v90, v91
	v_lshl_add_u64 v[182:183], v[182:183], 0, s[68:69]
	s_nop 0
	global_store_dwordx4 v[182:183], v[84:87], off
	v_exp_f32_e64 v152, -v76
	v_exp_f32_e64 v153, -v77
	v_exp_f32_e64 v178, -v78
	v_exp_f32_e64 v179, -v79
	v_exp_f32_e64 v246, -v72
	v_exp_f32_e64 v247, -v73
	v_exp_f32_e64 v248, -v74
	v_exp_f32_e64 v249, -v75
	v_mul_f32_e32 v76, v76, v68
	v_mul_f32_e32 v77, v77, v69
	v_mul_f32_e32 v78, v78, v70
	v_mul_f32_e32 v79, v79, v71
	v_mul_f32_e32 v72, v72, v64
	v_mul_f32_e32 v73, v73, v65
	v_mul_f32_e32 v74, v74, v66
	v_mul_f32_e32 v75, v75, v67
	v_add_f32_e32 v152, 1.0, v152
	v_add_f32_e32 v153, 1.0, v153
	v_add_f32_e32 v178, 1.0, v178
	v_add_f32_e32 v179, 1.0, v179
	v_add_f32_e32 v246, 1.0, v246
	v_add_f32_e32 v247, 1.0, v247
	v_add_f32_e32 v248, 1.0, v248
	v_add_f32_e32 v249, 1.0, v249
	v_rcp_f32_e32 v152, v152
	v_rcp_f32_e32 v153, v153
	v_rcp_f32_e32 v178, v178
	v_rcp_f32_e32 v179, v179
	v_rcp_f32_e32 v246, v246
	v_rcp_f32_e32 v247, v247
	v_rcp_f32_e32 v248, v248
	v_rcp_f32_e32 v249, v249
	v_mul_f32_e32 v76, v76, v152
	v_mul_f32_e32 v77, v77, v153
	v_mul_f32_e32 v78, v78, v178
	v_mul_f32_e32 v79, v79, v179
	v_mul_f32_e32 v72, v72, v246
	v_mul_f32_e32 v73, v73, v247
	v_mul_f32_e32 v74, v74, v248
	v_mul_f32_e32 v75, v75, v249
	v_cvt_pk_bf16_f32 v68, v76, v77
	v_cvt_pk_bf16_f32 v69, v78, v79
	v_cvt_pk_bf16_f32 v70, v72, v73
	v_cvt_pk_bf16_f32 v71, v74, v75
	v_lshl_add_u64 v[182:183], v[182:183], 0, s[68:69]
	s_nop 0
	global_store_dwordx4 v[182:183], v[68:71], off
	v_exp_f32_e64 v152, -v60
	v_exp_f32_e64 v153, -v61
	v_exp_f32_e64 v178, -v62
	v_exp_f32_e64 v179, -v63
	v_exp_f32_e64 v246, -v56
	v_exp_f32_e64 v247, -v57
	v_exp_f32_e64 v248, -v58
	v_exp_f32_e64 v249, -v59
	v_mul_f32_e32 v60, v60, v52
	v_mul_f32_e32 v61, v61, v53
	v_mul_f32_e32 v62, v62, v54
	v_mul_f32_e32 v63, v63, v55
	v_mul_f32_e32 v56, v56, v48
	v_mul_f32_e32 v57, v57, v49
	v_mul_f32_e32 v58, v58, v50
	v_mul_f32_e32 v59, v59, v51
	v_add_f32_e32 v152, 1.0, v152
	v_add_f32_e32 v153, 1.0, v153
	v_add_f32_e32 v178, 1.0, v178
	v_add_f32_e32 v179, 1.0, v179
	v_add_f32_e32 v246, 1.0, v246
	v_add_f32_e32 v247, 1.0, v247
	v_add_f32_e32 v248, 1.0, v248
	v_add_f32_e32 v249, 1.0, v249
	v_rcp_f32_e32 v152, v152
	v_rcp_f32_e32 v153, v153
	v_rcp_f32_e32 v178, v178
	v_rcp_f32_e32 v179, v179
	v_rcp_f32_e32 v246, v246
	v_rcp_f32_e32 v247, v247
	v_rcp_f32_e32 v248, v248
	v_rcp_f32_e32 v249, v249
	v_mul_f32_e32 v60, v60, v152
	v_mul_f32_e32 v61, v61, v153
	v_mul_f32_e32 v62, v62, v178
	v_mul_f32_e32 v63, v63, v179
	v_mul_f32_e32 v56, v56, v246
	v_mul_f32_e32 v57, v57, v247
	v_mul_f32_e32 v58, v58, v248
	v_mul_f32_e32 v59, v59, v249
	v_cvt_pk_bf16_f32 v52, v60, v61
	v_cvt_pk_bf16_f32 v53, v62, v63
	v_cvt_pk_bf16_f32 v54, v56, v57
	v_cvt_pk_bf16_f32 v55, v58, v59
	v_lshl_add_u64 v[182:183], v[182:183], 0, s[70:71]
	s_nop 0
	global_store_dwordx4 v[182:183], v[52:55], off
	v_exp_f32_e64 v152, -v44
	v_exp_f32_e64 v153, -v45
	v_exp_f32_e64 v178, -v46
	v_exp_f32_e64 v179, -v47
	v_exp_f32_e64 v246, -v40
	v_exp_f32_e64 v247, -v41
	v_exp_f32_e64 v248, -v42
	v_exp_f32_e64 v249, -v43
	v_mul_f32_e32 v44, v44, v36
	v_mul_f32_e32 v45, v45, v37
	v_mul_f32_e32 v46, v46, v38
	v_mul_f32_e32 v47, v47, v39
	v_mul_f32_e32 v40, v40, v32
	v_mul_f32_e32 v41, v41, v33
	v_mul_f32_e32 v42, v42, v34
	v_mul_f32_e32 v43, v43, v35
	v_add_f32_e32 v152, 1.0, v152
	v_add_f32_e32 v153, 1.0, v153
	v_add_f32_e32 v178, 1.0, v178
	v_add_f32_e32 v179, 1.0, v179
	v_add_f32_e32 v246, 1.0, v246
	v_add_f32_e32 v247, 1.0, v247
	v_add_f32_e32 v248, 1.0, v248
	v_add_f32_e32 v249, 1.0, v249
	v_rcp_f32_e32 v152, v152
	v_rcp_f32_e32 v153, v153
	v_rcp_f32_e32 v178, v178
	v_rcp_f32_e32 v179, v179
	v_rcp_f32_e32 v246, v246
	v_rcp_f32_e32 v247, v247
	v_rcp_f32_e32 v248, v248
	v_rcp_f32_e32 v249, v249
	v_mul_f32_e32 v44, v44, v152
	v_mul_f32_e32 v45, v45, v153
	v_mul_f32_e32 v46, v46, v178
	v_mul_f32_e32 v47, v47, v179
	v_mul_f32_e32 v40, v40, v246
	v_mul_f32_e32 v41, v41, v247
	v_mul_f32_e32 v42, v42, v248
	v_mul_f32_e32 v43, v43, v249
	v_cvt_pk_bf16_f32 v36, v44, v45
	v_cvt_pk_bf16_f32 v37, v46, v47
	v_cvt_pk_bf16_f32 v38, v40, v41
	v_cvt_pk_bf16_f32 v39, v42, v43
	v_lshl_add_u64 v[182:183], v[182:183], 0, s[68:69]
	s_nop 0
	global_store_dwordx4 v[182:183], v[36:39], off
	v_exp_f32_e64 v152, -v28
	v_exp_f32_e64 v153, -v29
	v_exp_f32_e64 v178, -v30
	v_exp_f32_e64 v179, -v31
	v_exp_f32_e64 v246, -v24
	v_exp_f32_e64 v247, -v25
	v_exp_f32_e64 v248, -v26
	v_exp_f32_e64 v249, -v27
	v_mul_f32_e32 v28, v28, v20
	v_mul_f32_e32 v29, v29, v21
	v_mul_f32_e32 v30, v30, v22
	v_mul_f32_e32 v31, v31, v23
	v_mul_f32_e32 v24, v24, v16
	v_mul_f32_e32 v25, v25, v17
	v_mul_f32_e32 v26, v26, v18
	v_mul_f32_e32 v27, v27, v19
	v_add_f32_e32 v152, 1.0, v152
	v_add_f32_e32 v153, 1.0, v153
	v_add_f32_e32 v178, 1.0, v178
	v_add_f32_e32 v179, 1.0, v179
	v_add_f32_e32 v246, 1.0, v246
	v_add_f32_e32 v247, 1.0, v247
	v_add_f32_e32 v248, 1.0, v248
	v_add_f32_e32 v249, 1.0, v249
	v_rcp_f32_e32 v152, v152
	v_rcp_f32_e32 v153, v153
	v_rcp_f32_e32 v178, v178
	v_rcp_f32_e32 v179, v179
	v_rcp_f32_e32 v246, v246
	v_rcp_f32_e32 v247, v247
	v_rcp_f32_e32 v248, v248
	v_rcp_f32_e32 v249, v249
	v_mul_f32_e32 v28, v28, v152
	v_mul_f32_e32 v29, v29, v153
	v_mul_f32_e32 v30, v30, v178
	v_mul_f32_e32 v31, v31, v179
	v_mul_f32_e32 v24, v24, v246
	v_mul_f32_e32 v25, v25, v247
	v_mul_f32_e32 v26, v26, v248
	v_mul_f32_e32 v27, v27, v249
	v_cvt_pk_bf16_f32 v20, v28, v29
	v_cvt_pk_bf16_f32 v21, v30, v31
	v_cvt_pk_bf16_f32 v22, v24, v25
	v_cvt_pk_bf16_f32 v23, v26, v27
	v_lshl_add_u64 v[182:183], v[182:183], 0, s[68:69]
	s_nop 0
	global_store_dwordx4 v[182:183], v[20:23], off
	v_exp_f32_e64 v152, -v12
	v_exp_f32_e64 v153, -v13
	v_exp_f32_e64 v178, -v14
	v_exp_f32_e64 v179, -v15
	v_exp_f32_e64 v246, -v8
	v_exp_f32_e64 v247, -v9
	v_exp_f32_e64 v248, -v10
	v_exp_f32_e64 v249, -v11
	v_mul_f32_e32 v12, v12, v4
	v_mul_f32_e32 v13, v13, v5
	v_mul_f32_e32 v14, v14, v6
	v_mul_f32_e32 v15, v15, v7
	v_mul_f32_e32 v8, v8, v0
	v_mul_f32_e32 v9, v9, v1
	v_mul_f32_e32 v10, v10, v2
	v_mul_f32_e32 v11, v11, v3
	v_add_f32_e32 v152, 1.0, v152
	v_add_f32_e32 v153, 1.0, v153
	v_add_f32_e32 v178, 1.0, v178
	v_add_f32_e32 v179, 1.0, v179
	v_add_f32_e32 v246, 1.0, v246
	v_add_f32_e32 v247, 1.0, v247
	v_add_f32_e32 v248, 1.0, v248
	v_add_f32_e32 v249, 1.0, v249
	v_rcp_f32_e32 v152, v152
	v_rcp_f32_e32 v153, v153
	v_rcp_f32_e32 v178, v178
	v_rcp_f32_e32 v179, v179
	v_rcp_f32_e32 v246, v246
	v_rcp_f32_e32 v247, v247
	v_rcp_f32_e32 v248, v248
	v_rcp_f32_e32 v249, v249
	v_mul_f32_e32 v12, v12, v152
	v_mul_f32_e32 v13, v13, v153
	v_mul_f32_e32 v14, v14, v178
	v_mul_f32_e32 v15, v15, v179
	v_mul_f32_e32 v8, v8, v246
	v_mul_f32_e32 v9, v9, v247
	v_mul_f32_e32 v10, v10, v248
	v_mul_f32_e32 v11, v11, v249
	v_cvt_pk_bf16_f32 v4, v12, v13
	v_cvt_pk_bf16_f32 v5, v14, v15
	v_cvt_pk_bf16_f32 v6, v8, v9
	v_cvt_pk_bf16_f32 v7, v10, v11
	v_lshl_add_u64 v[182:183], v[182:183], 0, s[68:69]
	s_nop 0
	global_store_dwordx4 v[182:183], v[4:7], off
	s_cbranch_vccnz .LBB0_209
	s_andn2_b64 vcc, exec, s[4:5]
	s_cbranch_vccnz .LBB0_208
	s_barrier
	s_branch .LBB0_208

.LBB0_1441:
	v_lshl_add_u32 v181, s1, 8, v154
	v_lshl_or_b32 v170, s0, 7, v156
	v_readlane_b32 s0, v254, 45
	v_readlane_b32 s1, v254, 46
	s_movk_i32 s3, 0x1600
	s_mov_b64 s[68:69], 0x16000
	s_mov_b64 s[70:71], 0x6e000
	s_andn2_b64 vcc, exec, s[40:41]
	s_mov_b64 s[16:17], -1
	v_ashrrev_i32_e32 v171, 31, v170
	v_mov_b64_e32 v[152:153], s[0:1]
	v_lshlrev_b64 v[170:171], 1, v[170:171]
	v_mad_i64_i32 v[182:183], s[0:1], v181, s3, v[152:153]
	s_nop 0
	v_lshl_add_u64 v[182:183], v[182:183], 0, v[170:171]
	v_exp_f32_e64 v152, -v124
	v_exp_f32_e64 v153, -v125
	v_exp_f32_e64 v178, -v126
	v_exp_f32_e64 v179, -v127
	v_exp_f32_e64 v246, -v120
	v_exp_f32_e64 v247, -v121
	v_exp_f32_e64 v248, -v122
	v_exp_f32_e64 v249, -v123
	v_mul_f32_e32 v124, v124, v116
	v_mul_f32_e32 v125, v125, v117
	v_mul_f32_e32 v126, v126, v118
	v_mul_f32_e32 v127, v127, v119
	v_mul_f32_e32 v120, v120, v112
	v_mul_f32_e32 v121, v121, v113
	v_mul_f32_e32 v122, v122, v114
	v_mul_f32_e32 v123, v123, v115
	v_add_f32_e32 v152, 1.0, v152
	v_add_f32_e32 v153, 1.0, v153
	v_add_f32_e32 v178, 1.0, v178
	v_add_f32_e32 v179, 1.0, v179
	v_add_f32_e32 v246, 1.0, v246
	v_add_f32_e32 v247, 1.0, v247
	v_add_f32_e32 v248, 1.0, v248
	v_add_f32_e32 v249, 1.0, v249
	v_rcp_f32_e32 v152, v152
	v_rcp_f32_e32 v153, v153
	v_rcp_f32_e32 v178, v178
	v_rcp_f32_e32 v179, v179
	v_rcp_f32_e32 v246, v246
	v_rcp_f32_e32 v247, v247
	v_rcp_f32_e32 v248, v248
	v_rcp_f32_e32 v249, v249
	v_mul_f32_e32 v124, v124, v152
	v_mul_f32_e32 v125, v125, v153
	v_mul_f32_e32 v126, v126, v178
	v_mul_f32_e32 v127, v127, v179
	v_mul_f32_e32 v120, v120, v246
	v_mul_f32_e32 v121, v121, v247
	v_mul_f32_e32 v122, v122, v248
	v_mul_f32_e32 v123, v123, v249
	v_cvt_pk_bf16_f32 v116, v124, v125
	v_cvt_pk_bf16_f32 v117, v126, v127
	v_cvt_pk_bf16_f32 v118, v120, v121
	v_cvt_pk_bf16_f32 v119, v122, v123
	global_store_dwordx4 v[182:183], v[116:119], off
	v_exp_f32_e64 v152, -v108
	v_exp_f32_e64 v153, -v109
	v_exp_f32_e64 v178, -v110
	v_exp_f32_e64 v179, -v111
	v_exp_f32_e64 v246, -v104
	v_exp_f32_e64 v247, -v105
	v_exp_f32_e64 v248, -v106
	v_exp_f32_e64 v249, -v107
	v_mul_f32_e32 v108, v108, v100
	v_mul_f32_e32 v109, v109, v101
	v_mul_f32_e32 v110, v110, v102
	v_mul_f32_e32 v111, v111, v103
	v_mul_f32_e32 v104, v104, v96
	v_mul_f32_e32 v105, v105, v97
	v_mul_f32_e32 v106, v106, v98
	v_mul_f32_e32 v107, v107, v99
	v_add_f32_e32 v152, 1.0, v152
	v_add_f32_e32 v153, 1.0, v153
	v_add_f32_e32 v178, 1.0, v178
	v_add_f32_e32 v179, 1.0, v179
	v_add_f32_e32 v246, 1.0, v246
	v_add_f32_e32 v247, 1.0, v247
	v_add_f32_e32 v248, 1.0, v248
	v_add_f32_e32 v249, 1.0, v249
	v_rcp_f32_e32 v152, v152
	v_rcp_f32_e32 v153, v153
	v_rcp_f32_e32 v178, v178
	v_rcp_f32_e32 v179, v179
	v_rcp_f32_e32 v246, v246
	v_rcp_f32_e32 v247, v247
	v_rcp_f32_e32 v248, v248
	v_rcp_f32_e32 v249, v249
	v_mul_f32_e32 v108, v108, v152
	v_mul_f32_e32 v109, v109, v153
	v_mul_f32_e32 v110, v110, v178
	v_mul_f32_e32 v111, v111, v179
	v_mul_f32_e32 v104, v104, v246
	v_mul_f32_e32 v105, v105, v247
	v_mul_f32_e32 v106, v106, v248
	v_mul_f32_e32 v107, v107, v249
	v_cvt_pk_bf16_f32 v100, v108, v109
	v_cvt_pk_bf16_f32 v101, v110, v111
	v_cvt_pk_bf16_f32 v102, v104, v105
	v_cvt_pk_bf16_f32 v103, v106, v107
	v_lshl_add_u64 v[182:183], v[182:183], 0, s[68:69]
	s_nop 0
	global_store_dwordx4 v[182:183], v[100:103], off
	v_exp_f32_e64 v152, -v92
	v_exp_f32_e64 v153, -v93
	v_exp_f32_e64 v178, -v94
	v_exp_f32_e64 v179, -v95
	v_exp_f32_e64 v246, -v88
	v_exp_f32_e64 v247, -v89
	v_exp_f32_e64 v248, -v90
	v_exp_f32_e64 v249, -v91
	v_mul_f32_e32 v92, v92, v84
	v_mul_f32_e32 v93, v93, v85
	v_mul_f32_e32 v94, v94, v86
	v_mul_f32_e32 v95, v95, v87
	v_mul_f32_e32 v88, v88, v80
	v_mul_f32_e32 v89, v89, v81
	v_mul_f32_e32 v90, v90, v82
	v_mul_f32_e32 v91, v91, v83
	v_add_f32_e32 v152, 1.0, v152
	v_add_f32_e32 v153, 1.0, v153
	v_add_f32_e32 v178, 1.0, v178
	v_add_f32_e32 v179, 1.0, v179
	v_add_f32_e32 v246, 1.0, v246
	v_add_f32_e32 v247, 1.0, v247
	v_add_f32_e32 v248, 1.0, v248
	v_add_f32_e32 v249, 1.0, v249
	v_rcp_f32_e32 v152, v152
	v_rcp_f32_e32 v153, v153
	v_rcp_f32_e32 v178, v178
	v_rcp_f32_e32 v179, v179
	v_rcp_f32_e32 v246, v246
	v_rcp_f32_e32 v247, v247
	v_rcp_f32_e32 v248, v248
	v_rcp_f32_e32 v249, v249
	v_mul_f32_e32 v92, v92, v152
	v_mul_f32_e32 v93, v93, v153
	v_mul_f32_e32 v94, v94, v178
	v_mul_f32_e32 v95, v95, v179
	v_mul_f32_e32 v88, v88, v246
	v_mul_f32_e32 v89, v89, v247
	v_mul_f32_e32 v90, v90, v248
	v_mul_f32_e32 v91, v91, v249
	v_cvt_pk_bf16_f32 v84, v92, v93
	v_cvt_pk_bf16_f32 v85, v94, v95
	v_cvt_pk_bf16_f32 v86, v88, v89
	v_cvt_pk_bf16_f32 v87, v90, v91
	v_lshl_add_u64 v[182:183], v[182:183], 0, s[68:69]
	s_nop 0
	global_store_dwordx4 v[182:183], v[84:87], off
	v_exp_f32_e64 v152, -v76
	v_exp_f32_e64 v153, -v77
	v_exp_f32_e64 v178, -v78
	v_exp_f32_e64 v179, -v79
	v_exp_f32_e64 v246, -v72
	v_exp_f32_e64 v247, -v73
	v_exp_f32_e64 v248, -v74
	v_exp_f32_e64 v249, -v75
	v_mul_f32_e32 v76, v76, v68
	v_mul_f32_e32 v77, v77, v69
	v_mul_f32_e32 v78, v78, v70
	v_mul_f32_e32 v79, v79, v71
	v_mul_f32_e32 v72, v72, v64
	v_mul_f32_e32 v73, v73, v65
	v_mul_f32_e32 v74, v74, v66
	v_mul_f32_e32 v75, v75, v67
	v_add_f32_e32 v152, 1.0, v152
	v_add_f32_e32 v153, 1.0, v153
	v_add_f32_e32 v178, 1.0, v178
	v_add_f32_e32 v179, 1.0, v179
	v_add_f32_e32 v246, 1.0, v246
	v_add_f32_e32 v247, 1.0, v247
	v_add_f32_e32 v248, 1.0, v248
	v_add_f32_e32 v249, 1.0, v249
	v_rcp_f32_e32 v152, v152
	v_rcp_f32_e32 v153, v153
	v_rcp_f32_e32 v178, v178
	v_rcp_f32_e32 v179, v179
	v_rcp_f32_e32 v246, v246
	v_rcp_f32_e32 v247, v247
	v_rcp_f32_e32 v248, v248
	v_rcp_f32_e32 v249, v249
	v_mul_f32_e32 v76, v76, v152
	v_mul_f32_e32 v77, v77, v153
	v_mul_f32_e32 v78, v78, v178
	v_mul_f32_e32 v79, v79, v179
	v_mul_f32_e32 v72, v72, v246
	v_mul_f32_e32 v73, v73, v247
	v_mul_f32_e32 v74, v74, v248
	v_mul_f32_e32 v75, v75, v249
	v_cvt_pk_bf16_f32 v68, v76, v77
	v_cvt_pk_bf16_f32 v69, v78, v79
	v_cvt_pk_bf16_f32 v70, v72, v73
	v_cvt_pk_bf16_f32 v71, v74, v75
	v_lshl_add_u64 v[182:183], v[182:183], 0, s[68:69]
	s_nop 0
	global_store_dwordx4 v[182:183], v[68:71], off
	v_exp_f32_e64 v152, -v60
	v_exp_f32_e64 v153, -v61
	v_exp_f32_e64 v178, -v62
	v_exp_f32_e64 v179, -v63
	v_exp_f32_e64 v246, -v56
	v_exp_f32_e64 v247, -v57
	v_exp_f32_e64 v248, -v58
	v_exp_f32_e64 v249, -v59
	v_mul_f32_e32 v60, v60, v52
	v_mul_f32_e32 v61, v61, v53
	v_mul_f32_e32 v62, v62, v54
	v_mul_f32_e32 v63, v63, v55
	v_mul_f32_e32 v56, v56, v48
	v_mul_f32_e32 v57, v57, v49
	v_mul_f32_e32 v58, v58, v50
	v_mul_f32_e32 v59, v59, v51
	v_add_f32_e32 v152, 1.0, v152
	v_add_f32_e32 v153, 1.0, v153
	v_add_f32_e32 v178, 1.0, v178
	v_add_f32_e32 v179, 1.0, v179
	v_add_f32_e32 v246, 1.0, v246
	v_add_f32_e32 v247, 1.0, v247
	v_add_f32_e32 v248, 1.0, v248
	v_add_f32_e32 v249, 1.0, v249
	v_rcp_f32_e32 v152, v152
	v_rcp_f32_e32 v153, v153
	v_rcp_f32_e32 v178, v178
	v_rcp_f32_e32 v179, v179
	v_rcp_f32_e32 v246, v246
	v_rcp_f32_e32 v247, v247
	v_rcp_f32_e32 v248, v248
	v_rcp_f32_e32 v249, v249
	v_mul_f32_e32 v60, v60, v152
	v_mul_f32_e32 v61, v61, v153
	v_mul_f32_e32 v62, v62, v178
	v_mul_f32_e32 v63, v63, v179
	v_mul_f32_e32 v56, v56, v246
	v_mul_f32_e32 v57, v57, v247
	v_mul_f32_e32 v58, v58, v248
	v_mul_f32_e32 v59, v59, v249
	v_cvt_pk_bf16_f32 v52, v60, v61
	v_cvt_pk_bf16_f32 v53, v62, v63
	v_cvt_pk_bf16_f32 v54, v56, v57
	v_cvt_pk_bf16_f32 v55, v58, v59
	v_lshl_add_u64 v[182:183], v[182:183], 0, s[70:71]
	s_nop 0
	global_store_dwordx4 v[182:183], v[52:55], off
	v_exp_f32_e64 v152, -v44
	v_exp_f32_e64 v153, -v45
	v_exp_f32_e64 v178, -v46
	v_exp_f32_e64 v179, -v47
	v_exp_f32_e64 v246, -v40
	v_exp_f32_e64 v247, -v41
	v_exp_f32_e64 v248, -v42
	v_exp_f32_e64 v249, -v43
	v_mul_f32_e32 v44, v44, v36
	v_mul_f32_e32 v45, v45, v37
	v_mul_f32_e32 v46, v46, v38
	v_mul_f32_e32 v47, v47, v39
	v_mul_f32_e32 v40, v40, v32
	v_mul_f32_e32 v41, v41, v33
	v_mul_f32_e32 v42, v42, v34
	v_mul_f32_e32 v43, v43, v35
	v_add_f32_e32 v152, 1.0, v152
	v_add_f32_e32 v153, 1.0, v153
	v_add_f32_e32 v178, 1.0, v178
	v_add_f32_e32 v179, 1.0, v179
	v_add_f32_e32 v246, 1.0, v246
	v_add_f32_e32 v247, 1.0, v247
	v_add_f32_e32 v248, 1.0, v248
	v_add_f32_e32 v249, 1.0, v249
	v_rcp_f32_e32 v152, v152
	v_rcp_f32_e32 v153, v153
	v_rcp_f32_e32 v178, v178
	v_rcp_f32_e32 v179, v179
	v_rcp_f32_e32 v246, v246
	v_rcp_f32_e32 v247, v247
	v_rcp_f32_e32 v248, v248
	v_rcp_f32_e32 v249, v249
	v_mul_f32_e32 v44, v44, v152
	v_mul_f32_e32 v45, v45, v153
	v_mul_f32_e32 v46, v46, v178
	v_mul_f32_e32 v47, v47, v179
	v_mul_f32_e32 v40, v40, v246
	v_mul_f32_e32 v41, v41, v247
	v_mul_f32_e32 v42, v42, v248
	v_mul_f32_e32 v43, v43, v249
	v_cvt_pk_bf16_f32 v36, v44, v45
	v_cvt_pk_bf16_f32 v37, v46, v47
	v_cvt_pk_bf16_f32 v38, v40, v41
	v_cvt_pk_bf16_f32 v39, v42, v43
	v_lshl_add_u64 v[182:183], v[182:183], 0, s[68:69]
	s_nop 0
	global_store_dwordx4 v[182:183], v[36:39], off
	v_exp_f32_e64 v152, -v28
	v_exp_f32_e64 v153, -v29
	v_exp_f32_e64 v178, -v30
	v_exp_f32_e64 v179, -v31
	v_exp_f32_e64 v246, -v24
	v_exp_f32_e64 v247, -v25
	v_exp_f32_e64 v248, -v26
	v_exp_f32_e64 v249, -v27
	v_mul_f32_e32 v28, v28, v20
	v_mul_f32_e32 v29, v29, v21
	v_mul_f32_e32 v30, v30, v22
	v_mul_f32_e32 v31, v31, v23
	v_mul_f32_e32 v24, v24, v16
	v_mul_f32_e32 v25, v25, v17
	v_mul_f32_e32 v26, v26, v18
	v_mul_f32_e32 v27, v27, v19
	v_add_f32_e32 v152, 1.0, v152
	v_add_f32_e32 v153, 1.0, v153
	v_add_f32_e32 v178, 1.0, v178
	v_add_f32_e32 v179, 1.0, v179
	v_add_f32_e32 v246, 1.0, v246
	v_add_f32_e32 v247, 1.0, v247
	v_add_f32_e32 v248, 1.0, v248
	v_add_f32_e32 v249, 1.0, v249
	v_rcp_f32_e32 v152, v152
	v_rcp_f32_e32 v153, v153
	v_rcp_f32_e32 v178, v178
	v_rcp_f32_e32 v179, v179
	v_rcp_f32_e32 v246, v246
	v_rcp_f32_e32 v247, v247
	v_rcp_f32_e32 v248, v248
	v_rcp_f32_e32 v249, v249
	v_mul_f32_e32 v28, v28, v152
	v_mul_f32_e32 v29, v29, v153
	v_mul_f32_e32 v30, v30, v178
	v_mul_f32_e32 v31, v31, v179
	v_mul_f32_e32 v24, v24, v246
	v_mul_f32_e32 v25, v25, v247
	v_mul_f32_e32 v26, v26, v248
	v_mul_f32_e32 v27, v27, v249
	v_cvt_pk_bf16_f32 v20, v28, v29
	v_cvt_pk_bf16_f32 v21, v30, v31
	v_cvt_pk_bf16_f32 v22, v24, v25
	v_cvt_pk_bf16_f32 v23, v26, v27
	v_lshl_add_u64 v[182:183], v[182:183], 0, s[68:69]
	s_nop 0
	global_store_dwordx4 v[182:183], v[20:23], off
	v_exp_f32_e64 v152, -v12
	v_exp_f32_e64 v153, -v13
	v_exp_f32_e64 v178, -v14
	v_exp_f32_e64 v179, -v15
	v_exp_f32_e64 v246, -v8
	v_exp_f32_e64 v247, -v9
	v_exp_f32_e64 v248, -v10
	v_exp_f32_e64 v249, -v11
	v_mul_f32_e32 v12, v12, v4
	v_mul_f32_e32 v13, v13, v5
	v_mul_f32_e32 v14, v14, v6
	v_mul_f32_e32 v15, v15, v7
	v_mul_f32_e32 v8, v8, v0
	v_mul_f32_e32 v9, v9, v1
	v_mul_f32_e32 v10, v10, v2
	v_mul_f32_e32 v11, v11, v3
	v_add_f32_e32 v152, 1.0, v152
	v_add_f32_e32 v153, 1.0, v153
	v_add_f32_e32 v178, 1.0, v178
	v_add_f32_e32 v179, 1.0, v179
	v_add_f32_e32 v246, 1.0, v246
	v_add_f32_e32 v247, 1.0, v247
	v_add_f32_e32 v248, 1.0, v248
	v_add_f32_e32 v249, 1.0, v249
	v_rcp_f32_e32 v152, v152
	v_rcp_f32_e32 v153, v153
	v_rcp_f32_e32 v178, v178
	v_rcp_f32_e32 v179, v179
	v_rcp_f32_e32 v246, v246
	v_rcp_f32_e32 v247, v247
	v_rcp_f32_e32 v248, v248
	v_rcp_f32_e32 v249, v249
	v_mul_f32_e32 v12, v12, v152
	v_mul_f32_e32 v13, v13, v153
	v_mul_f32_e32 v14, v14, v178
	v_mul_f32_e32 v15, v15, v179
	v_mul_f32_e32 v8, v8, v246
	v_mul_f32_e32 v9, v9, v247
	v_mul_f32_e32 v10, v10, v248
	v_mul_f32_e32 v11, v11, v249
	v_cvt_pk_bf16_f32 v4, v12, v13
	v_cvt_pk_bf16_f32 v5, v14, v15
	v_cvt_pk_bf16_f32 v6, v8, v9
	v_cvt_pk_bf16_f32 v7, v10, v11
	v_lshl_add_u64 v[182:183], v[182:183], 0, s[68:69]
	s_nop 0
	global_store_dwordx4 v[182:183], v[4:7], off
	s_cbranch_vccnz .LBB0_1434
	s_andn2_b64 vcc, exec, s[4:5]
	s_cbranch_vccnz .LBB0_1433
	s_barrier
	s_branch .LBB0_1433
